# attention phase without the static wave-half priority raise
# baseline (speedup 1.0000x reference)
.LBB0_106:
	s_andn2_b64 vcc, exec, s[8:9]
	s_cbranch_vccnz .LBB0_273
	v_readlane_b32 s2, v254, 36
	s_cmp_gt_i32 s2, 3
	s_cbranch_scc1 .LBB0_109
	s_nop 0
